# adaLN GEMV for modulation cols>=4096 deferred into attention queue (32 units + in-unit reduction), on top of conv units IL=4
# baseline (speedup 1.0000x reference)
; __device__ __forceinline__ float sigmoidf_(float x) { return __builtin_amdgcn_rcpf(1.0f + __builtin_amdgcn_exp2f(-1.4426950408889634f * x)); }
; __global__ void __launch_bounds__(512, 2) fwd_kernel(Args a) {
;     ...
;         for (int it = gw; it < NITEMS; it += NGW) {
;             int r = it;
;             if (r < I_ADA) {
;                 const int cb = r % 48, kc = r / 48, col = cb * 256 + lane * 4;
;                 f32x4 s0 = {0.f, 0.f, 0.f, 0.f}, s1 = {0.f, 0.f, 0.f, 0.f};
;                 const int kbeg = kc * (DMODEL / KC_ADA);
; #pragma unroll 16
;                 for (int k = kbeg; k < kbeg + DMODEL / KC_ADA; ++k) {
;                     const f32x4 wv = __builtin_nontemporal_load((const f32x4*)(wada_p + (size_t)k * NADA + col));
;                     const float c0 = c_p[k], c1 = c_p[DMODEL + k];
;                     const float a0 = c0 * sigmoidf_(c0), a1 = c1 * sigmoidf_(c1);
;                     s0 += wv * a0; s1 += wv * a1;
;                 }
;                 *(f32x4*)(part + (size_t)(kc * 2 + 0) * NADA + col) = s0; *(f32x4*)(part + (size_t)(kc * 2 + 1) * NADA + col) = s1;
;                 continue;
;             }
.LBB0_25:
	s_cmp_lg_u32 s100, 0
	s_cbranch_scc1 .Lp0_noskip
	s_cmpk_gt_i32 s79, 0x5ff
	s_cbranch_scc1 .Lp0_noskip
	s_mul_i32 s0, s79, 0x556
	s_lshr_b32 s0, s0, 16
	s_mul_i32 s0, s0, 48
	s_sub_i32 s0, s79, s0
	s_cmp_gt_u32 s0, 15
	s_cbranch_scc1 .LBB0_24

; __global__ void __launch_bounds__(512, 2) fwd_kernel(Args a) {
;     ...
;         for (int it = gw; it < NITEMS; it += NGW) {
;             int r = it;
;             if (r < I_ADA) {
;                 const int cb = r % 48, kc = r / 48, col = cb * 256 + lane * 4;
;                 f32x4 s0 = {0.f, 0.f, 0.f, 0.f}, s1 = {0.f, 0.f, 0.f, 0.f};
;                 const int kbeg = kc * (DMODEL / KC_ADA);
; #pragma unroll 16
;                 for (int k = kbeg; k < kbeg + DMODEL / KC_ADA; ++k) {
;     ...
;         for (int e = bx * 512 + tid; e < 2 * NADA; e += G * 512) { const int b = e / NADA, n = e % NADA; float s = bada_p[n];
; #pragma unroll
;             for (int kc = 0; kc < KC_ADA; ++kc) s += part[(size_t)(kc * 2 + b) * NADA + n];
;             mod[e] = s; }
.Lcv_unit:
	v_readfirstlane_b32 s0, v0
	s_lshr_b32 s0, s0, 6
	s_cmp_lt_u32 s1, 32
	s_cbranch_scc0 .Lcv_conv
	s_add_i32 s98, s1, 16
	s_mul_i32 s0, s0, 48
	s_add_i32 s99, s98, s0
	s_add_i32 s101, s98, 0x5d0
	s_movk_i32 s97, 0x180
	s_branch .Lcv_save
.Lcv_conv:
	s_sub_i32 s1, s1, 32
	s_mov_b32 s98, 0
	s_lshl_b32 s1, s1, 6
	s_addk_i32 s1, 0x1600
	s_add_i32 s99, s1, s0
	s_add_i32 s101, s1, 63
	s_movk_i32 s97, 8
.Lcv_save:
	v_writelane_b32 v248, s2, 0
	v_writelane_b32 v248, s3, 1
	v_writelane_b32 v248, s4, 2
	v_writelane_b32 v248, s5, 3
	v_writelane_b32 v248, s6, 4
	v_writelane_b32 v248, s7, 5
	v_writelane_b32 v248, s8, 6
	v_writelane_b32 v248, s9, 7
	v_writelane_b32 v248, s10, 8
	v_writelane_b32 v248, s11, 9
	v_writelane_b32 v248, s12, 10
	v_writelane_b32 v248, s13, 11
	v_writelane_b32 v248, s14, 12
	v_writelane_b32 v248, s15, 13
	v_writelane_b32 v248, s16, 14
	v_writelane_b32 v248, s17, 15
	v_writelane_b32 v248, s18, 16
	v_writelane_b32 v248, s19, 17
	v_writelane_b32 v248, s20, 18
	v_writelane_b32 v248, s21, 19
	v_writelane_b32 v248, s22, 20
	v_writelane_b32 v248, s23, 21
	v_writelane_b32 v248, s24, 22
	v_writelane_b32 v248, s25, 23
	v_writelane_b32 v248, s26, 24
	v_writelane_b32 v248, s27, 25
	v_writelane_b32 v248, s28, 26
	v_writelane_b32 v248, s29, 27
	v_writelane_b32 v248, s30, 28
	v_writelane_b32 v248, s31, 29
	v_writelane_b32 v248, s32, 30
	v_writelane_b32 v248, s33, 31
	v_writelane_b32 v248, s34, 32
	v_writelane_b32 v248, s35, 33
	v_writelane_b32 v248, s36, 34
	v_writelane_b32 v248, s37, 35
	v_writelane_b32 v248, s38, 36
	v_writelane_b32 v248, s39, 37
	v_writelane_b32 v248, s40, 38
	v_writelane_b32 v248, s41, 39
	v_writelane_b32 v248, s42, 40
	v_writelane_b32 v248, s43, 41
	v_writelane_b32 v248, s44, 42
	v_writelane_b32 v248, s45, 43
	v_writelane_b32 v248, s46, 44
	v_writelane_b32 v248, s47, 45
	v_writelane_b32 v248, s48, 46
	v_writelane_b32 v248, s49, 47
	v_writelane_b32 v248, s50, 48
	v_writelane_b32 v248, s51, 49
	v_writelane_b32 v248, s52, 50
	v_writelane_b32 v248, s53, 51
	v_writelane_b32 v248, s54, 52
	v_writelane_b32 v248, s55, 53
	v_writelane_b32 v248, s56, 54
	v_writelane_b32 v248, s57, 55
	v_writelane_b32 v248, s58, 56
	v_writelane_b32 v248, s59, 57
	v_writelane_b32 v248, s60, 58
	v_writelane_b32 v248, s61, 59
	v_writelane_b32 v248, s62, 60
	v_writelane_b32 v248, s63, 61
	v_writelane_b32 v248, s64, 62
	v_writelane_b32 v248, s65, 63
	v_writelane_b32 v249, s66, 0
	v_writelane_b32 v249, s67, 1
	v_writelane_b32 v249, s68, 2
	v_writelane_b32 v249, s69, 3
	v_writelane_b32 v249, s70, 4
	v_writelane_b32 v249, s71, 5
	v_writelane_b32 v249, s72, 6
	v_writelane_b32 v249, s73, 7
	v_writelane_b32 v249, s74, 8
	v_writelane_b32 v249, s75, 9
	v_writelane_b32 v249, s76, 10
	v_writelane_b32 v249, s77, 11
	v_writelane_b32 v249, s78, 12
	v_writelane_b32 v249, s79, 13
	v_writelane_b32 v249, s80, 14
	v_mov_b32_e32 v236, v146
	v_mov_b32_e32 v237, v147
	v_mov_b32_e32 v238, v148
	v_mov_b32_e32 v239, v149
	v_mov_b32_e32 v240, v150
	v_mov_b32_e32 v241, v151
	v_mov_b32_e32 v242, v152
	v_mov_b32_e32 v243, v153
	v_mov_b32_e32 v244, v154
	v_mov_b32_e32 v245, v155
	v_mov_b32_e32 v246, v156
	v_mov_b32_e32 v247, v167
	v_mov_b32_e32 v192, v157
	v_mov_b32_e32 v193, v158
	v_mov_b32_e32 v194, v159
	v_mov_b32_e32 v195, v160
	v_mov_b32_e32 v198, v161
	v_mov_b32_e32 v199, v162
	v_mov_b32_e32 v200, v163
	v_mov_b32_e32 v201, v164
	v_mov_b32_e32 v202, v165
	v_mov_b32_e32 v203, v166
	v_mov_b32_e32 v204, v168
	v_mov_b32_e32 v205, v169
	v_mov_b32_e32 v206, v170
	v_mov_b32_e32 v207, v171
	v_mov_b32_e32 v208, v172
	v_mov_b32_e32 v209, v173
	v_mov_b32_e32 v210, v174
	v_mov_b32_e32 v214, v175
	v_mov_b32_e32 v215, v176
	v_mov_b32_e32 v216, v177
	v_mov_b32_e32 v217, v178
	v_readfirstlane_b32 s50, v0
	s_lshr_b32 s50, s50, 6
	s_mov_b32 s14, s97
	v_readlane_b32 s97, v255, 39
	s_mov_b32 s100, 1
	s_branch .Lp0_entry
.Lcv_ret:
	s_cmp_eq_u32 s98, 0
	s_cbranch_scc1 .Lcv_nored
	s_waitcnt vmcnt(0)
	s_barrier
	s_add_i32 s0, 0, 0x220a0
	v_mov_b32_e32 v2, s0
	ds_read_b64 v[2:3], v2
	s_add_i32 s0, 0, 0x22018
	v_mov_b32_e32 v4, s0
	ds_read_b64 v[4:5], v4
	s_waitcnt lgkmcnt(0)
	v_readfirstlane_b32 s2, v2
	v_readfirstlane_b32 s3, v3
	v_readfirstlane_b32 s4, v4
	v_readfirstlane_b32 s5, v5
	v_and_b32_e32 v6, 0xff, v0
	v_mov_b32_e32 v7, s98
	v_lshl_or_b32 v6, v7, 8, v6
	v_lshrrev_b32_e32 v8, 8, v0
	v_lshlrev_b32_e32 v9, 2, v6
	global_load_dword v10, v9, s[4:5]
	v_mul_u32_u24_e32 v11, 0xc000, v8
	v_add_u32_e32 v11, v11, v9
	s_add_u32 s6, s2, 0x15400000
	s_addc_u32 s7, s3, 0
	global_load_dword v12, v11, s[6:7] sc1
	s_add_u32 s6, s6, 0x18000
	s_addc_u32 s7, s7, 0
	global_load_dword v13, v11, s[6:7] sc1
	s_add_u32 s6, s6, 0x18000
	s_addc_u32 s7, s7, 0
	global_load_dword v14, v11, s[6:7] sc1
	s_add_u32 s6, s6, 0x18000
	s_addc_u32 s7, s7, 0
	global_load_dword v15, v11, s[6:7] sc1
	s_add_u32 s6, s6, 0x18000
	s_addc_u32 s7, s7, 0
	global_load_dword v16, v11, s[6:7] sc1
	s_add_u32 s6, s6, 0x18000
	s_addc_u32 s7, s7, 0
	global_load_dword v17, v11, s[6:7] sc1
	s_add_u32 s6, s6, 0x18000
	s_addc_u32 s7, s7, 0
	global_load_dword v18, v11, s[6:7] sc1
	s_add_u32 s6, s6, 0x18000
	s_addc_u32 s7, s7, 0
	global_load_dword v19, v11, s[6:7] sc1
	s_add_u32 s6, s6, 0x18000
	s_addc_u32 s7, s7, 0
	global_load_dword v20, v11, s[6:7] sc1
	s_add_u32 s6, s6, 0x18000
	s_addc_u32 s7, s7, 0
	global_load_dword v21, v11, s[6:7] sc1
	s_add_u32 s6, s6, 0x18000
	s_addc_u32 s7, s7, 0
	global_load_dword v22, v11, s[6:7] sc1
	s_add_u32 s6, s6, 0x18000
	s_addc_u32 s7, s7, 0
	global_load_dword v23, v11, s[6:7] sc1
	s_add_u32 s6, s6, 0x18000
	s_addc_u32 s7, s7, 0
	global_load_dword v24, v11, s[6:7] sc1
	s_add_u32 s6, s6, 0x18000
; __global__ void __launch_bounds__(512, 2) fwd_kernel(Args a) {
;     ...
;         for (int e = bx * 512 + tid; e < 2 * NADA; e += G * 512) { const int b = e / NADA, n = e % NADA; float s = bada_p[n];
; #pragma unroll
;             for (int kc = 0; kc < KC_ADA; ++kc) s += part[(size_t)(kc * 2 + b) * NADA + n];
;             mod[e] = s; }
	s_addc_u32 s7, s7, 0
	global_load_dword v25, v11, s[6:7] sc1
	s_add_u32 s6, s6, 0x18000
	s_addc_u32 s7, s7, 0
	global_load_dword v26, v11, s[6:7] sc1
	s_add_u32 s6, s6, 0x18000
	s_addc_u32 s7, s7, 0
	global_load_dword v27, v11, s[6:7] sc1
	s_add_u32 s6, s6, 0x18000
	s_addc_u32 s7, s7, 0
	global_load_dword v28, v11, s[6:7] sc1
	s_add_u32 s6, s6, 0x18000
	s_addc_u32 s7, s7, 0
	global_load_dword v29, v11, s[6:7] sc1
	s_add_u32 s6, s6, 0x18000
	s_addc_u32 s7, s7, 0
	global_load_dword v30, v11, s[6:7] sc1
	s_add_u32 s6, s6, 0x18000
	s_addc_u32 s7, s7, 0
	global_load_dword v31, v11, s[6:7] sc1
	s_add_u32 s6, s6, 0x18000
	s_addc_u32 s7, s7, 0
	global_load_dword v32, v11, s[6:7] sc1
	s_add_u32 s6, s6, 0x18000
	s_addc_u32 s7, s7, 0
	global_load_dword v33, v11, s[6:7] sc1
	s_add_u32 s6, s6, 0x18000
	s_addc_u32 s7, s7, 0
	global_load_dword v34, v11, s[6:7] sc1
	s_add_u32 s6, s6, 0x18000
	s_addc_u32 s7, s7, 0
	global_load_dword v35, v11, s[6:7] sc1
	s_add_u32 s6, s6, 0x18000
	s_addc_u32 s7, s7, 0
	global_load_dword v36, v11, s[6:7] sc1
	s_add_u32 s6, s6, 0x18000
	s_addc_u32 s7, s7, 0
	global_load_dword v37, v11, s[6:7] sc1
	s_add_u32 s6, s6, 0x18000
	s_addc_u32 s7, s7, 0
	global_load_dword v38, v11, s[6:7] sc1
	s_add_u32 s6, s6, 0x18000
	s_addc_u32 s7, s7, 0
	global_load_dword v39, v11, s[6:7] sc1
	s_add_u32 s6, s6, 0x18000
	s_addc_u32 s7, s7, 0
	global_load_dword v40, v11, s[6:7] sc1
	s_add_u32 s6, s6, 0x18000
	s_addc_u32 s7, s7, 0
	global_load_dword v41, v11, s[6:7] sc1
	s_add_u32 s6, s6, 0x18000
	s_addc_u32 s7, s7, 0
	global_load_dword v42, v11, s[6:7] sc1
	s_add_u32 s6, s6, 0x18000
	s_addc_u32 s7, s7, 0
	global_load_dword v43, v11, s[6:7] sc1
	s_add_u32 s6, s6, 0x18000
	s_addc_u32 s7, s7, 0
	s_waitcnt vmcnt(0)
	v_add_f32_e32 v10, v10, v12
	v_add_f32_e32 v10, v10, v13
	v_add_f32_e32 v10, v10, v14
	v_add_f32_e32 v10, v10, v15
	v_add_f32_e32 v10, v10, v16
	v_add_f32_e32 v10, v10, v17
	v_add_f32_e32 v10, v10, v18
	v_add_f32_e32 v10, v10, v19
	v_add_f32_e32 v10, v10, v20
	v_add_f32_e32 v10, v10, v21
	v_add_f32_e32 v10, v10, v22
	v_add_f32_e32 v10, v10, v23
	v_add_f32_e32 v10, v10, v24
	v_add_f32_e32 v10, v10, v25
	v_add_f32_e32 v10, v10, v26
	v_add_f32_e32 v10, v10, v27
	v_add_f32_e32 v10, v10, v28
	v_add_f32_e32 v10, v10, v29
	v_add_f32_e32 v10, v10, v30
	v_add_f32_e32 v10, v10, v31
	v_add_f32_e32 v10, v10, v32
	v_add_f32_e32 v10, v10, v33
	v_add_f32_e32 v10, v10, v34
	v_add_f32_e32 v10, v10, v35
	v_add_f32_e32 v10, v10, v36
	v_add_f32_e32 v10, v10, v37
	v_add_f32_e32 v10, v10, v38
	v_add_f32_e32 v10, v10, v39
	v_add_f32_e32 v10, v10, v40
	v_add_f32_e32 v10, v10, v41
	v_add_f32_e32 v10, v10, v42
	v_add_f32_e32 v10, v10, v43
	s_add_u32 s6, s2, 0x100000
	s_addc_u32 s7, s3, 0
	global_store_dword v11, v10, s[6:7]
.Lcv_nored:
	v_mov_b32_e32 v146, v236
	v_mov_b32_e32 v147, v237
	v_mov_b32_e32 v148, v238
	v_mov_b32_e32 v149, v239
	v_mov_b32_e32 v150, v240
	v_mov_b32_e32 v151, v241
	v_mov_b32_e32 v152, v242
	v_mov_b32_e32 v153, v243
	v_mov_b32_e32 v154, v244
	v_mov_b32_e32 v155, v245
	v_mov_b32_e32 v156, v246
	v_mov_b32_e32 v167, v247
	v_mov_b32_e32 v157, v192
	v_mov_b32_e32 v158, v193
	v_mov_b32_e32 v159, v194
	v_mov_b32_e32 v160, v195
	v_mov_b32_e32 v161, v198
	v_mov_b32_e32 v162, v199
	v_mov_b32_e32 v163, v200
	v_mov_b32_e32 v164, v201
	v_mov_b32_e32 v165, v202
	v_mov_b32_e32 v166, v203
	v_mov_b32_e32 v168, v204
	v_mov_b32_e32 v169, v205
	v_mov_b32_e32 v170, v206
	v_mov_b32_e32 v171, v207
	v_mov_b32_e32 v172, v208
	v_mov_b32_e32 v173, v209
	v_mov_b32_e32 v174, v210
	v_mov_b32_e32 v175, v214
	v_mov_b32_e32 v176, v215
	v_mov_b32_e32 v177, v216
	v_mov_b32_e32 v178, v217
	v_readlane_b32 s2, v248, 0
	v_readlane_b32 s3, v248, 1
	v_readlane_b32 s4, v248, 2
	v_readlane_b32 s5, v248, 3
	v_readlane_b32 s6, v248, 4
	v_readlane_b32 s7, v248, 5
	v_readlane_b32 s8, v248, 6
	v_readlane_b32 s9, v248, 7
	v_readlane_b32 s10, v248, 8
	v_readlane_b32 s11, v248, 9
	v_readlane_b32 s12, v248, 10
	v_readlane_b32 s13, v248, 11
	v_readlane_b32 s14, v248, 12
	v_readlane_b32 s15, v248, 13
	v_readlane_b32 s16, v248, 14
	v_readlane_b32 s17, v248, 15
	v_readlane_b32 s18, v248, 16
	v_readlane_b32 s19, v248, 17
	v_readlane_b32 s20, v248, 18
	v_readlane_b32 s21, v248, 19
	v_readlane_b32 s22, v248, 20
	v_readlane_b32 s23, v248, 21
	v_readlane_b32 s24, v248, 22
	v_readlane_b32 s25, v248, 23
	v_readlane_b32 s26, v248, 24
	v_readlane_b32 s27, v248, 25
	v_readlane_b32 s28, v248, 26
	v_readlane_b32 s29, v248, 27
	v_readlane_b32 s30, v248, 28
	v_readlane_b32 s31, v248, 29
	v_readlane_b32 s32, v248, 30
	v_readlane_b32 s33, v248, 31
	v_readlane_b32 s34, v248, 32
	v_readlane_b32 s35, v248, 33
	v_readlane_b32 s36, v248, 34
	v_readlane_b32 s37, v248, 35
	v_readlane_b32 s38, v248, 36
	v_readlane_b32 s39, v248, 37
	v_readlane_b32 s40, v248, 38
	v_readlane_b32 s41, v248, 39
	v_readlane_b32 s42, v248, 40
	v_readlane_b32 s43, v248, 41
	v_readlane_b32 s44, v248, 42
	v_readlane_b32 s45, v248, 43
	v_readlane_b32 s46, v248, 44
	v_readlane_b32 s47, v248, 45
	v_readlane_b32 s48, v248, 46
	v_readlane_b32 s49, v248, 47
	v_readlane_b32 s50, v248, 48
	v_readlane_b32 s51, v248, 49
	v_readlane_b32 s52, v248, 50
	v_readlane_b32 s53, v248, 51
	v_readlane_b32 s54, v248, 52
	v_readlane_b32 s55, v248, 53
	v_readlane_b32 s56, v248, 54
	v_readlane_b32 s57, v248, 55
	v_readlane_b32 s58, v248, 56
	v_readlane_b32 s59, v248, 57
	v_readlane_b32 s60, v248, 58
	v_readlane_b32 s61, v248, 59
	v_readlane_b32 s62, v248, 60
	v_readlane_b32 s63, v248, 61
	v_readlane_b32 s64, v248, 62
	v_readlane_b32 s65, v248, 63
	v_readlane_b32 s66, v249, 0
	v_readlane_b32 s67, v249, 1
	v_readlane_b32 s68, v249, 2
	v_readlane_b32 s69, v249, 3
	v_readlane_b32 s70, v249, 4
	v_readlane_b32 s71, v249, 5
	v_readlane_b32 s72, v249, 6
	v_readlane_b32 s73, v249, 7
	v_readlane_b32 s74, v249, 8
	v_readlane_b32 s75, v249, 9
	v_readlane_b32 s76, v249, 10
	v_readlane_b32 s77, v249, 11
	v_readlane_b32 s78, v249, 12
	v_readlane_b32 s79, v249, 13
	v_readlane_b32 s80, v249, 14
	s_waitcnt lgkmcnt(0)
	s_barrier
	s_branch .LBB0_641

; __global__ void __launch_bounds__(512, 2) fwd_kernel(Args a) {
;     ...
;         for (;;) {
;             if (tid == 0) *qw = atomicAdd(ctl + 64 * rep, 1u);
;             __syncthreads();
;             const unsigned idx = *qw;
;             __syncthreads();
;             if (idx >= 768u) break;
;             const int level = idx / 48, rr = idx % 48, qb = 15 - level;
.LBB0_647:
	s_or_b64 exec, exec, s[0:1]
	v_mov_b32_e32 v2, s38
	s_waitcnt vmcnt(0) lgkmcnt(0)
	s_barrier
	ds_read_b32 v2, v2
	s_movk_i32 s0, 0x3bf
	s_waitcnt lgkmcnt(0)
	s_barrier
	v_cmp_lt_u32_e32 vcc, s0, v2
	v_readfirstlane_b32 s6, v2
	s_mov_b64 s[0:1], -1
	s_cbranch_vccnz .LBB0_642
	s_cmp_gt_u32 s6, 0x2ff
	s_cbranch_scc1 .Ldq_tail
	s_and_b32 s0, s6, 3
	s_lshr_b32 s1, s6, 2
	s_cmp_eq_u32 s0, 3
	s_cbranch_scc1 .Lcv_unit
	s_mul_i32 s1, s1, 3
	s_add_i32 s6, s1, s0
	s_branch .Ldq_go
.Ldq_tail:
	s_sub_i32 s6, s6, 0xc0
